# adaLN path load order changed to cond, ada_w, weight-copy item: the 32 copy-item loads issue after the 64 ada_w loads; counted waits adjusted
# baseline (speedup 1.0000x reference)
.LBB0_55:
	v_and_b32_e32 v109, 31, v2
	v_lshl_or_b32 v8, s3, 5, v109
	s_mov_b32 s27, 0x2aaaaaab
	v_mul_hi_i32 v1, v8, s27
	v_lshrrev_b32_e32 v3, 31, v1
	v_ashrrev_i32_e32 v1, 9, v1
	v_add_u32_e32 v15, v1, v3
	s_waitcnt lgkmcnt(0)
	v_lshlrev_b32_e32 v112, 2, v0
	v_mov_b32_e32 v113, 0
	s_mov_b64 s[98:99], 0x1000
	v_lshl_add_u64 v[114:115], s[36:37], 0, v[112:113]
	v_lshl_add_u64 v[112:113], s[34:35], 0, v[112:113]
	global_load_dword v126, v[114:115], off
	global_load_dword v127, v[114:115], off offset:2048
	v_lshl_add_u64 v[114:115], v[114:115], 0, s[98:99]
	global_load_dword v128, v[114:115], off
	global_load_dword v129, v[114:115], off offset:2048
	v_lshl_add_u64 v[114:115], v[114:115], 0, s[98:99]
	global_load_dword v130, v[114:115], off
	global_load_dword v131, v[114:115], off offset:2048
	v_lshl_add_u64 v[114:115], v[114:115], 0, s[98:99]
	global_load_dword v132, v[114:115], off
	global_load_dword v133, v[114:115], off offset:2048
	v_lshl_add_u64 v[114:115], v[114:115], 0, s[98:99]
	global_load_dword v134, v[114:115], off
	global_load_dword v135, v[114:115], off offset:2048
	v_lshl_add_u64 v[114:115], v[114:115], 0, s[98:99]
	global_load_dword v136, v[114:115], off
	global_load_dword v137, v[114:115], off offset:2048
	v_lshl_add_u64 v[114:115], v[114:115], 0, s[98:99]
	global_load_dword v138, v[114:115], off
	global_load_dword v139, v[114:115], off offset:2048
	v_lshl_add_u64 v[114:115], v[114:115], 0, s[98:99]
	global_load_dword v140, v[114:115], off
	global_load_dword v141, v[114:115], off offset:2048
	global_load_dword v142, v[112:113], off
	global_load_dword v143, v[112:113], off offset:2048
	v_lshlrev_b32_e32 v114, 2, v8
	v_mov_b32_e32 v115, 0
	v_lshl_add_u64 v[114:115], s[12:13], 0, v[114:115]
	global_load_dword v144, v[114:115], off
	v_mov_b64_e32 v[4:5], s[40:41]
	s_and_b64 s[40:41], s[4:5], exec
	v_mul_i32_i24_e32 v1, 0xc00, v15
	s_mov_b32 s27, 0xc00000
	s_cselect_b32 s31, s15, s31
	s_cselect_b32 s39, s14, s30
	s_ashr_i32 s43, s42, 31
	v_sub_u32_e32 v6, v8, v1
	v_mad_i64_i32 v[4:5], s[40:41], v15, s27, v[4:5]
	s_lshl_b32 s30, s26, 6
	s_lshl_b64 s[26:27], s[42:43], 2
	v_ashrrev_i32_e32 v7, 31, v6
	v_ashrrev_i32_e32 v3, 5, v2
	s_add_u32 s26, s39, s26
	v_mov_b32_e32 v11, 0
	v_lshl_add_u64 v[12:13], v[6:7], 2, v[4:5]
	v_add_u32_e32 v1, s30, v3
	s_addc_u32 s27, s31, s27
	v_lshlrev_b32_e32 v4, 2, v109
	v_mov_b32_e32 v5, v11
	v_lshl_add_u64 v[38:39], s[26:27], 0, v[4:5]
	v_mad_i64_i32 v[16:17], s[26:27], s38, v1, 0
	v_add_u32_e32 v5, 2, v1
	v_lshl_add_u64 v[148:149], v[16:17], 2, v[38:39]
	v_mad_i64_i32 v[16:17], s[26:27], s38, v5, 0
	v_add_u32_e32 v5, 4, v1
	v_lshl_add_u64 v[150:151], v[16:17], 2, v[38:39]
	v_mad_i64_i32 v[16:17], s[26:27], s38, v5, 0
	v_add_u32_e32 v5, 6, v1
	v_lshl_add_u64 v[152:153], v[16:17], 2, v[38:39]
	v_mad_i64_i32 v[16:17], s[26:27], s38, v5, 0
	v_add_u32_e32 v5, 8, v1
	v_lshl_add_u64 v[154:155], v[16:17], 2, v[38:39]
	v_mad_i64_i32 v[16:17], s[26:27], s38, v5, 0
	v_add_u32_e32 v5, 10, v1
	v_lshl_add_u64 v[156:157], v[16:17], 2, v[38:39]
	v_mad_i64_i32 v[16:17], s[26:27], s38, v5, 0
	v_add_u32_e32 v5, 12, v1
	v_lshl_add_u64 v[158:159], v[16:17], 2, v[38:39]
	v_mad_i64_i32 v[16:17], s[26:27], s38, v5, 0
	v_add_u32_e32 v5, 14, v1
	v_lshl_add_u64 v[160:161], v[16:17], 2, v[38:39]
	v_mad_i64_i32 v[16:17], s[26:27], s38, v5, 0
	v_add_u32_e32 v9, 16, v1
	v_lshl_add_u64 v[162:163], v[16:17], 2, v[38:39]
	v_mad_i64_i32 v[22:23], s[26:27], s38, v9, 0
	v_add_u32_e32 v9, 18, v1
	v_lshl_add_u64 v[164:165], v[22:23], 2, v[38:39]
	v_mad_i64_i32 v[22:23], s[26:27], s38, v9, 0
	v_add_u32_e32 v9, 20, v1
	v_lshl_add_u64 v[166:167], v[22:23], 2, v[38:39]
	v_mad_i64_i32 v[22:23], s[26:27], s38, v9, 0
	v_add_u32_e32 v9, 22, v1
	v_lshl_add_u64 v[168:169], v[22:23], 2, v[38:39]
	v_mad_i64_i32 v[22:23], s[26:27], s38, v9, 0
	v_add_u32_e32 v9, 24, v1
	v_lshl_add_u64 v[170:171], v[22:23], 2, v[38:39]
	v_mad_i64_i32 v[22:23], s[26:27], s38, v9, 0
	v_add_u32_e32 v9, 26, v1
	v_lshl_add_u64 v[172:173], v[22:23], 2, v[38:39]
	v_mad_i64_i32 v[22:23], s[26:27], s38, v9, 0
	v_add_u32_e32 v9, 28, v1
	v_lshl_add_u64 v[174:175], v[22:23], 2, v[38:39]
	v_mad_i64_i32 v[22:23], s[26:27], s38, v9, 0
	v_add_u32_e32 v9, 30, v1
	v_lshl_add_u64 v[176:177], v[22:23], 2, v[38:39]
	v_mad_i64_i32 v[22:23], s[26:27], s38, v9, 0
	v_add_u32_e32 v9, 32, v1
	v_lshl_add_u64 v[178:179], v[22:23], 2, v[38:39]
	v_mad_i64_i32 v[30:31], s[26:27], s38, v9, 0
	v_add_u32_e32 v9, 34, v1
	v_lshl_add_u64 v[180:181], v[30:31], 2, v[38:39]
	v_mad_i64_i32 v[30:31], s[26:27], s38, v9, 0
	v_add_u32_e32 v9, 36, v1
	v_lshl_add_u64 v[182:183], v[30:31], 2, v[38:39]
	v_mad_i64_i32 v[30:31], s[26:27], s38, v9, 0
	v_add_u32_e32 v9, 38, v1
	v_lshl_add_u64 v[184:185], v[30:31], 2, v[38:39]
	v_mad_i64_i32 v[30:31], s[26:27], s38, v9, 0
	v_add_u32_e32 v9, 40, v1
	v_lshl_add_u64 v[186:187], v[30:31], 2, v[38:39]
	v_mad_i64_i32 v[30:31], s[26:27], s38, v9, 0
	v_add_u32_e32 v9, 42, v1
	v_lshl_add_u64 v[188:189], v[30:31], 2, v[38:39]
	v_mad_i64_i32 v[30:31], s[26:27], s38, v9, 0
	v_add_u32_e32 v9, 44, v1
	v_lshl_add_u64 v[190:191], v[30:31], 2, v[38:39]
	v_mad_i64_i32 v[30:31], s[26:27], s38, v9, 0
	v_add_u32_e32 v9, 46, v1
	v_lshl_add_u64 v[192:193], v[30:31], 2, v[38:39]
	v_mad_i64_i32 v[30:31], s[26:27], s38, v9, 0
	v_add_u32_e32 v9, 48, v1
	v_lshl_add_u64 v[194:195], v[30:31], 2, v[38:39]
	v_mad_i64_i32 v[40:41], s[26:27], s38, v9, 0
	v_add_u32_e32 v9, 50, v1
	v_lshl_add_u64 v[196:197], v[40:41], 2, v[38:39]
	v_mad_i64_i32 v[40:41], s[26:27], s38, v9, 0
	v_add_u32_e32 v9, 52, v1
	v_lshl_add_u64 v[198:199], v[40:41], 2, v[38:39]
	v_mad_i64_i32 v[40:41], s[26:27], s38, v9, 0
	v_add_u32_e32 v9, 54, v1
	v_lshl_add_u64 v[200:201], v[40:41], 2, v[38:39]
	v_mad_i64_i32 v[40:41], s[26:27], s38, v9, 0
	v_add_u32_e32 v9, 56, v1
	v_lshl_add_u64 v[202:203], v[40:41], 2, v[38:39]
	v_mad_i64_i32 v[40:41], s[26:27], s38, v9, 0
	v_add_u32_e32 v9, 58, v1
	v_lshl_add_u64 v[204:205], v[40:41], 2, v[38:39]
	v_mad_i64_i32 v[40:41], s[26:27], s38, v9, 0
	v_add_u32_e32 v9, 60, v1
	v_ashrrev_i32_e32 v14, 5, v0
	v_lshl_add_u64 v[206:207], v[40:41], 2, v[38:39]
	v_mad_i64_i32 v[40:41], s[26:27], s38, v9, 0
	v_add_u32_e32 v1, 62, v1
	v_lshl_add_u64 v[208:209], v[40:41], 2, v[38:39]
	v_mad_i64_i32 v[40:41], s[26:27], s38, v1, 0
	v_lshlrev_b32_e32 v1, 6, v14
	s_movk_i32 s26, 0x3000
	v_or_b32_e32 v9, 1, v1
	v_lshl_add_u64 v[210:211], v[40:41], 2, v[38:39]
	v_mad_i64_i32 v[56:57], s[38:39], v9, s26, v[12:13]
	v_or_b32_e32 v9, 2, v1
	v_mad_i64_i32 v[58:59], s[38:39], v9, s26, v[12:13]
	v_or_b32_e32 v9, 3, v1
	v_mad_i64_i32 v[60:61], s[38:39], v9, s26, v[12:13]
	v_or_b32_e32 v9, 4, v1
	v_mad_i64_i32 v[62:63], s[38:39], v9, s26, v[12:13]
	v_or_b32_e32 v9, 5, v1
	v_mad_i64_i32 v[64:65], s[38:39], v9, s26, v[12:13]
	v_or_b32_e32 v9, 6, v1
	v_mad_i64_i32 v[54:55], s[38:39], v1, s26, v[12:13]
	v_mad_i64_i32 v[66:67], s[38:39], v9, s26, v[12:13]
	v_or_b32_e32 v9, 7, v1
	v_or_b32_e32 v10, 8, v1
	v_mad_i64_i32 v[68:69], s[38:39], v9, s26, v[12:13]
	global_load_dword v50, v[54:55], off nt
	global_load_dword v52, v[56:57], off nt
	global_load_dword v51, v[58:59], off nt
	global_load_dword v48, v[60:61], off nt
	global_load_dword v46, v[62:63], off nt
	global_load_dword v49, v[64:65], off nt
	global_load_dword v47, v[66:67], off nt
	global_load_dword v9, v[68:69], off nt
	v_mad_i64_i32 v[62:63], s[38:39], v10, s26, v[12:13]
	v_or_b32_e32 v10, 9, v1
	v_mad_i64_i32 v[64:65], s[38:39], v10, s26, v[12:13]
	v_or_b32_e32 v10, 10, v1
	v_mad_i64_i32 v[66:67], s[38:39], v10, s26, v[12:13]
	v_or_b32_e32 v10, 11, v1
	v_mad_i64_i32 v[68:69], s[38:39], v10, s26, v[12:13]
	v_or_b32_e32 v10, 12, v1
	v_mad_i64_i32 v[70:71], s[38:39], v10, s26, v[12:13]
	v_or_b32_e32 v10, 13, v1
	v_mad_i64_i32 v[72:73], s[38:39], v10, s26, v[12:13]
	v_or_b32_e32 v10, 14, v1
	v_mad_i64_i32 v[74:75], s[38:39], v10, s26, v[12:13]
	v_or_b32_e32 v10, 15, v1
	v_mad_i64_i32 v[76:77], s[38:39], v10, s26, v[12:13]
	v_or_b32_e32 v10, 16, v1
	global_load_dword v58, v[62:63], off nt
	global_load_dword v60, v[64:65], off nt
	global_load_dword v59, v[66:67], off nt
	global_load_dword v56, v[68:69], off nt
	global_load_dword v55, v[70:71], off nt
	global_load_dword v57, v[72:73], off nt
	global_load_dword v53, v[74:75], off nt
	global_load_dword v54, v[76:77], off nt
	v_mad_i64_i32 v[70:71], s[38:39], v10, s26, v[12:13]
	v_or_b32_e32 v10, 17, v1
	v_mad_i64_i32 v[72:73], s[38:39], v10, s26, v[12:13]
	v_or_b32_e32 v10, 18, v1
	v_mad_i64_i32 v[74:75], s[38:39], v10, s26, v[12:13]
	v_or_b32_e32 v10, 19, v1
	v_mad_i64_i32 v[76:77], s[38:39], v10, s26, v[12:13]
	v_or_b32_e32 v10, 20, v1
	v_mad_i64_i32 v[78:79], s[38:39], v10, s26, v[12:13]
	v_or_b32_e32 v10, 21, v1
	v_mad_i64_i32 v[80:81], s[38:39], v10, s26, v[12:13]
	v_or_b32_e32 v10, 22, v1
	v_mad_i64_i32 v[82:83], s[38:39], v10, s26, v[12:13]
	v_or_b32_e32 v10, 23, v1
	v_mad_i64_i32 v[84:85], s[38:39], v10, s26, v[12:13]
	v_or_b32_e32 v10, 24, v1
	global_load_dword v64, v[70:71], off nt
	global_load_dword v68, v[72:73], off nt
	global_load_dword v65, v[74:75], off nt
	global_load_dword v66, v[76:77], off nt
	global_load_dword v63, v[78:79], off nt
	global_load_dword v67, v[80:81], off nt
	global_load_dword v61, v[82:83], off nt
	global_load_dword v62, v[84:85], off nt
	v_mad_i64_i32 v[78:79], s[38:39], v10, s26, v[12:13]
	v_or_b32_e32 v10, 25, v1
	v_mad_i64_i32 v[80:81], s[38:39], v10, s26, v[12:13]
	v_or_b32_e32 v10, 26, v1
	v_mad_i64_i32 v[82:83], s[38:39], v10, s26, v[12:13]
	v_or_b32_e32 v10, 27, v1
	v_mad_i64_i32 v[84:85], s[38:39], v10, s26, v[12:13]
	v_or_b32_e32 v10, 28, v1
	v_mad_i64_i32 v[86:87], s[38:39], v10, s26, v[12:13]
	v_or_b32_e32 v10, 29, v1
	v_mad_i64_i32 v[88:89], s[38:39], v10, s26, v[12:13]
	v_or_b32_e32 v10, 30, v1
	v_mad_i64_i32 v[90:91], s[38:39], v10, s26, v[12:13]
	v_or_b32_e32 v10, 31, v1
	v_mad_i64_i32 v[92:93], s[38:39], v10, s26, v[12:13]
	v_or_b32_e32 v10, 32, v1
	global_load_dword v72, v[78:79], off nt
	global_load_dword v76, v[80:81], off nt
	global_load_dword v73, v[82:83], off nt
	global_load_dword v74, v[84:85], off nt
	global_load_dword v71, v[86:87], off nt
	global_load_dword v75, v[88:89], off nt
	global_load_dword v69, v[90:91], off nt
	global_load_dword v70, v[92:93], off nt
	v_mad_i64_i32 v[86:87], s[38:39], v10, s26, v[12:13]
	v_or_b32_e32 v10, 33, v1
	v_mad_i64_i32 v[88:89], s[38:39], v10, s26, v[12:13]
	v_or_b32_e32 v10, 34, v1
	v_mad_i64_i32 v[90:91], s[38:39], v10, s26, v[12:13]
	v_or_b32_e32 v10, 35, v1
	v_mad_i64_i32 v[92:93], s[38:39], v10, s26, v[12:13]
	v_or_b32_e32 v10, 36, v1
	v_mad_i64_i32 v[94:95], s[38:39], v10, s26, v[12:13]
	v_or_b32_e32 v10, 37, v1
	v_mad_i64_i32 v[96:97], s[38:39], v10, s26, v[12:13]
	v_or_b32_e32 v10, 38, v1
	v_mad_i64_i32 v[98:99], s[38:39], v10, s26, v[12:13]
	v_or_b32_e32 v10, 39, v1
	v_mad_i64_i32 v[100:101], s[38:39], v10, s26, v[12:13]
	v_or_b32_e32 v10, 40, v1
	global_load_dword v80, v[86:87], off nt
	global_load_dword v84, v[88:89], off nt
	global_load_dword v81, v[90:91], off nt
	global_load_dword v82, v[92:93], off nt
	global_load_dword v79, v[94:95], off nt
	global_load_dword v83, v[96:97], off nt
	global_load_dword v77, v[98:99], off nt
	global_load_dword v78, v[100:101], off nt
	v_mad_i64_i32 v[94:95], s[38:39], v10, s26, v[12:13]
	v_or_b32_e32 v10, 41, v1
	v_mad_i64_i32 v[96:97], s[38:39], v10, s26, v[12:13]
	v_or_b32_e32 v10, 42, v1
	v_mad_i64_i32 v[98:99], s[38:39], v10, s26, v[12:13]
	v_or_b32_e32 v10, 43, v1
	v_mad_i64_i32 v[100:101], s[38:39], v10, s26, v[12:13]
	v_or_b32_e32 v10, 44, v1
	v_mad_i64_i32 v[102:103], s[38:39], v10, s26, v[12:13]
	v_or_b32_e32 v10, 45, v1
	v_mad_i64_i32 v[104:105], s[38:39], v10, s26, v[12:13]
	v_or_b32_e32 v10, 46, v1
	v_mad_i64_i32 v[106:107], s[38:39], v10, s26, v[12:13]
	v_or_b32_e32 v10, 47, v1
	v_mad_i64_i32 v[110:111], s[38:39], v10, s26, v[12:13]
	v_or_b32_e32 v10, 48, v1
	global_load_dword v88, v[94:95], off nt
	global_load_dword v92, v[96:97], off nt
	global_load_dword v89, v[98:99], off nt
	global_load_dword v90, v[100:101], off nt
	global_load_dword v87, v[102:103], off nt
	global_load_dword v91, v[104:105], off nt
	global_load_dword v85, v[106:107], off nt
	global_load_dword v86, v[110:111], off nt
	v_mad_i64_i32 v[102:103], s[38:39], v10, s26, v[12:13]
	v_or_b32_e32 v10, 49, v1
	v_mad_i64_i32 v[104:105], s[38:39], v10, s26, v[12:13]
	v_or_b32_e32 v10, 50, v1
	v_mad_i64_i32 v[106:107], s[38:39], v10, s26, v[12:13]
	v_or_b32_e32 v10, 51, v1
	v_mad_i64_i32 v[110:111], s[38:39], v10, s26, v[12:13]
	v_or_b32_e32 v10, 52, v1
	v_mad_i64_i32 v[112:113], s[38:39], v10, s26, v[12:13]
	v_or_b32_e32 v10, 53, v1
	v_mad_i64_i32 v[114:115], s[38:39], v10, s26, v[12:13]
	v_or_b32_e32 v10, 54, v1
	v_mad_i64_i32 v[116:117], s[38:39], v10, s26, v[12:13]
	v_or_b32_e32 v10, 55, v1
	v_mad_i64_i32 v[118:119], s[38:39], v10, s26, v[12:13]
	v_or_b32_e32 v10, 56, v1
	global_load_dword v96, v[102:103], off nt
	global_load_dword v100, v[104:105], off nt
	global_load_dword v97, v[106:107], off nt
	global_load_dword v98, v[110:111], off nt
	global_load_dword v95, v[112:113], off nt
	global_load_dword v99, v[114:115], off nt
	global_load_dword v93, v[116:117], off nt
	global_load_dword v94, v[118:119], off nt
	v_or_b32_e32 v101, 57, v1
	v_or_b32_e32 v102, 58, v1
	v_or_b32_e32 v103, 59, v1
	v_or_b32_e32 v104, 60, v1
	v_or_b32_e32 v105, 61, v1
	v_or_b32_e32 v106, 62, v1
	v_or_b32_e32 v1, 63, v1
	v_mad_i64_i32 v[110:111], s[38:39], v10, s26, v[12:13]
	v_mad_i64_i32 v[112:113], s[38:39], v101, s26, v[12:13]
	v_mad_i64_i32 v[114:115], s[38:39], v102, s26, v[12:13]
	v_mad_i64_i32 v[116:117], s[38:39], v103, s26, v[12:13]
	v_mad_i64_i32 v[118:119], s[38:39], v104, s26, v[12:13]
	v_mad_i64_i32 v[120:121], s[38:39], v105, s26, v[12:13]
	v_mad_i64_i32 v[122:123], s[38:39], v106, s26, v[12:13]
	v_mad_i64_i32 v[12:13], s[26:27], v1, s26, v[12:13]
	global_load_dword v104, v[110:111], off nt
	global_load_dword v108, v[112:113], off nt
	global_load_dword v105, v[114:115], off nt
	global_load_dword v106, v[116:117], off nt
	global_load_dword v102, v[118:119], off nt
	global_load_dword v107, v[120:121], off nt
	global_load_dword v103, v[122:123], off nt
	global_load_dword v101, v[12:13], off nt
	global_load_dword v5, v[148:149], off nt
	global_load_dword v7, v[150:151], off nt
	global_load_dword v16, v[152:153], off nt
	global_load_dword v18, v[154:155], off nt
	global_load_dword v17, v[156:157], off nt
	global_load_dword v19, v[158:159], off nt
	global_load_dword v20, v[160:161], off nt
	global_load_dword v21, v[162:163], off nt
	global_load_dword v22, v[164:165], off nt
	global_load_dword v23, v[166:167], off nt
	global_load_dword v24, v[168:169], off nt
	global_load_dword v26, v[170:171], off nt
	global_load_dword v25, v[172:173], off nt
	global_load_dword v27, v[174:175], off nt
	global_load_dword v28, v[176:177], off nt
	global_load_dword v29, v[178:179], off nt
	global_load_dword v30, v[180:181], off nt
	global_load_dword v31, v[182:183], off nt
	global_load_dword v32, v[184:185], off nt
	global_load_dword v34, v[186:187], off nt
	global_load_dword v33, v[188:189], off nt
	global_load_dword v35, v[190:191], off nt
	global_load_dword v36, v[192:193], off nt
	global_load_dword v37, v[194:195], off nt
	global_load_dword v38, v[196:197], off nt
	global_load_dword v39, v[198:199], off nt
	global_load_dword v40, v[200:201], off nt
	global_load_dword v42, v[202:203], off nt
	global_load_dword v41, v[204:205], off nt
	global_load_dword v43, v[206:207], off nt
	global_load_dword v44, v[208:209], off nt
	global_load_dword v45, v[210:211], off nt
	s_movk_i32 s26, 0x2400
	v_cmp_gt_i32_e32 vcc, s26, v0
	s_and_saveexec_b64 s[38:39], vcc
	s_cbranch_execz .LBB0_58
	s_lshl_b32 s26, s75, 8
	v_lshl_add_u32 v110, v2, 2, s26
	s_waitcnt vmcnt(63)
	v_mul_f32_e32 v111, 0xbfb8aa3b, v126
	v_exp_f32_e32 v111, v111
	s_nop 0
	v_add_f32_e32 v111, 1.0, v111
	v_div_scale_f32 v112, s[42:43], v111, v111, v126
	v_rcp_f32_e32 v113, v112
	v_div_scale_f32 v114, vcc, v126, v111, v126
	v_fma_f32 v115, -v112, v113, 1.0
	v_fmac_f32_e32 v113, v115, v113
	v_mul_f32_e32 v115, v114, v113
	v_fma_f32 v116, -v112, v115, v114
	v_fmac_f32_e32 v115, v116, v113
	v_fma_f32 v112, -v112, v115, v114
	v_div_fmas_f32 v112, v112, v113, v115
	v_div_fixup_f32 v10, v112, v111, v126
	ds_write_b32 v110, v10
	v_mul_f32_e32 v111, 0xbfb8aa3b, v127
	v_exp_f32_e32 v111, v111
	s_nop 0
	v_add_f32_e32 v111, 1.0, v111
	v_div_scale_f32 v112, s[42:43], v111, v111, v127
	v_rcp_f32_e32 v113, v112
	v_div_scale_f32 v114, vcc, v127, v111, v127
	v_fma_f32 v115, -v112, v113, 1.0
	v_fmac_f32_e32 v113, v115, v113
	v_mul_f32_e32 v115, v114, v113
	v_fma_f32 v116, -v112, v115, v114
	v_fmac_f32_e32 v115, v116, v113
	v_fma_f32 v112, -v112, v115, v114
	v_div_fmas_f32 v112, v112, v113, v115
	v_div_fixup_f32 v10, v112, v111, v127
	ds_write_b32 v110, v10 offset:2048
	v_mul_f32_e32 v111, 0xbfb8aa3b, v128
	v_exp_f32_e32 v111, v111
	s_nop 0
	v_add_f32_e32 v111, 1.0, v111
	v_div_scale_f32 v112, s[42:43], v111, v111, v128
	v_rcp_f32_e32 v113, v112
	v_div_scale_f32 v114, vcc, v128, v111, v128
	v_fma_f32 v115, -v112, v113, 1.0
	v_fmac_f32_e32 v113, v115, v113
	v_mul_f32_e32 v115, v114, v113
	v_fma_f32 v116, -v112, v115, v114
	v_fmac_f32_e32 v115, v116, v113
	v_fma_f32 v112, -v112, v115, v114
	v_div_fmas_f32 v112, v112, v113, v115
	v_div_fixup_f32 v10, v112, v111, v128
	ds_write_b32 v110, v10 offset:4096
	v_mul_f32_e32 v111, 0xbfb8aa3b, v129
	v_exp_f32_e32 v111, v111
	s_nop 0
	v_add_f32_e32 v111, 1.0, v111
	v_div_scale_f32 v112, s[42:43], v111, v111, v129
	v_rcp_f32_e32 v113, v112
	v_div_scale_f32 v114, vcc, v129, v111, v129
	v_fma_f32 v115, -v112, v113, 1.0
	v_fmac_f32_e32 v113, v115, v113
	v_mul_f32_e32 v115, v114, v113
	v_fma_f32 v116, -v112, v115, v114
	v_fmac_f32_e32 v115, v116, v113
	v_fma_f32 v112, -v112, v115, v114
	v_div_fmas_f32 v112, v112, v113, v115
	v_div_fixup_f32 v10, v112, v111, v129
	ds_write_b32 v110, v10 offset:6144
	v_mul_f32_e32 v111, 0xbfb8aa3b, v130
	v_exp_f32_e32 v111, v111
	s_nop 0
	v_add_f32_e32 v111, 1.0, v111
	v_div_scale_f32 v112, s[42:43], v111, v111, v130
	v_rcp_f32_e32 v113, v112
	v_div_scale_f32 v114, vcc, v130, v111, v130
	v_fma_f32 v115, -v112, v113, 1.0
	v_fmac_f32_e32 v113, v115, v113
	v_mul_f32_e32 v115, v114, v113
	v_fma_f32 v116, -v112, v115, v114
	v_fmac_f32_e32 v115, v116, v113
	v_fma_f32 v112, -v112, v115, v114
	v_div_fmas_f32 v112, v112, v113, v115
	v_div_fixup_f32 v10, v112, v111, v130
	ds_write_b32 v110, v10 offset:8192
	v_mul_f32_e32 v111, 0xbfb8aa3b, v131
	v_exp_f32_e32 v111, v111
	s_nop 0
	v_add_f32_e32 v111, 1.0, v111
	v_div_scale_f32 v112, s[42:43], v111, v111, v131
	v_rcp_f32_e32 v113, v112
	v_div_scale_f32 v114, vcc, v131, v111, v131
	v_fma_f32 v115, -v112, v113, 1.0
	v_fmac_f32_e32 v113, v115, v113
	v_mul_f32_e32 v115, v114, v113
	v_fma_f32 v116, -v112, v115, v114
	v_fmac_f32_e32 v115, v116, v113
	v_fma_f32 v112, -v112, v115, v114
	v_div_fmas_f32 v112, v112, v113, v115
	v_div_fixup_f32 v10, v112, v111, v131
	ds_write_b32 v110, v10 offset:10240
	v_mul_f32_e32 v111, 0xbfb8aa3b, v132
	v_exp_f32_e32 v111, v111
	s_nop 0
	v_add_f32_e32 v111, 1.0, v111
	v_div_scale_f32 v112, s[42:43], v111, v111, v132
	v_rcp_f32_e32 v113, v112
	v_div_scale_f32 v114, vcc, v132, v111, v132
	v_fma_f32 v115, -v112, v113, 1.0
	v_fmac_f32_e32 v113, v115, v113
	v_mul_f32_e32 v115, v114, v113
	v_fma_f32 v116, -v112, v115, v114
	v_fmac_f32_e32 v115, v116, v113
	v_fma_f32 v112, -v112, v115, v114
	v_div_fmas_f32 v112, v112, v113, v115
	v_div_fixup_f32 v10, v112, v111, v132
	ds_write_b32 v110, v10 offset:12288
	v_mul_f32_e32 v111, 0xbfb8aa3b, v133
	v_exp_f32_e32 v111, v111
	s_nop 0
	v_add_f32_e32 v111, 1.0, v111
	v_div_scale_f32 v112, s[42:43], v111, v111, v133
	v_rcp_f32_e32 v113, v112
	v_div_scale_f32 v114, vcc, v133, v111, v133
	v_fma_f32 v115, -v112, v113, 1.0
	v_fmac_f32_e32 v113, v115, v113
	v_mul_f32_e32 v115, v114, v113
	v_fma_f32 v116, -v112, v115, v114
	v_fmac_f32_e32 v115, v116, v113
	v_fma_f32 v112, -v112, v115, v114
	v_div_fmas_f32 v112, v112, v113, v115
	v_div_fixup_f32 v10, v112, v111, v133
	ds_write_b32 v110, v10 offset:14336
	v_mul_f32_e32 v111, 0xbfb8aa3b, v134
	v_exp_f32_e32 v111, v111
	s_nop 0
	v_add_f32_e32 v111, 1.0, v111
	v_div_scale_f32 v112, s[42:43], v111, v111, v134
	v_rcp_f32_e32 v113, v112
	v_div_scale_f32 v114, vcc, v134, v111, v134
	v_fma_f32 v115, -v112, v113, 1.0
	v_fmac_f32_e32 v113, v115, v113
	v_mul_f32_e32 v115, v114, v113
	v_fma_f32 v116, -v112, v115, v114
	v_fmac_f32_e32 v115, v116, v113
	v_fma_f32 v112, -v112, v115, v114
	v_div_fmas_f32 v112, v112, v113, v115
	v_div_fixup_f32 v10, v112, v111, v134
	ds_write_b32 v110, v10 offset:16384
	v_mul_f32_e32 v111, 0xbfb8aa3b, v135
	v_exp_f32_e32 v111, v111
	s_nop 0
	v_add_f32_e32 v111, 1.0, v111
	v_div_scale_f32 v112, s[42:43], v111, v111, v135
	v_rcp_f32_e32 v113, v112
	v_div_scale_f32 v114, vcc, v135, v111, v135
	v_fma_f32 v115, -v112, v113, 1.0
	v_fmac_f32_e32 v113, v115, v113
	v_mul_f32_e32 v115, v114, v113
	v_fma_f32 v116, -v112, v115, v114
	v_fmac_f32_e32 v115, v116, v113
	v_fma_f32 v112, -v112, v115, v114
	v_div_fmas_f32 v112, v112, v113, v115
	v_div_fixup_f32 v10, v112, v111, v135
	ds_write_b32 v110, v10 offset:18432
	v_mul_f32_e32 v111, 0xbfb8aa3b, v136
	v_exp_f32_e32 v111, v111
	s_nop 0
	v_add_f32_e32 v111, 1.0, v111
	v_div_scale_f32 v112, s[42:43], v111, v111, v136
	v_rcp_f32_e32 v113, v112
	v_div_scale_f32 v114, vcc, v136, v111, v136
	v_fma_f32 v115, -v112, v113, 1.0
	v_fmac_f32_e32 v113, v115, v113
	v_mul_f32_e32 v115, v114, v113
	v_fma_f32 v116, -v112, v115, v114
	v_fmac_f32_e32 v115, v116, v113
	v_fma_f32 v112, -v112, v115, v114
	v_div_fmas_f32 v112, v112, v113, v115
	v_div_fixup_f32 v10, v112, v111, v136
	ds_write_b32 v110, v10 offset:20480
	v_mul_f32_e32 v111, 0xbfb8aa3b, v137
	v_exp_f32_e32 v111, v111
	s_nop 0
	v_add_f32_e32 v111, 1.0, v111
	v_div_scale_f32 v112, s[42:43], v111, v111, v137
	v_rcp_f32_e32 v113, v112
	v_div_scale_f32 v114, vcc, v137, v111, v137
	v_fma_f32 v115, -v112, v113, 1.0
	v_fmac_f32_e32 v113, v115, v113
	v_mul_f32_e32 v115, v114, v113
	v_fma_f32 v116, -v112, v115, v114
	v_fmac_f32_e32 v115, v116, v113
	v_fma_f32 v112, -v112, v115, v114
	v_div_fmas_f32 v112, v112, v113, v115
	v_div_fixup_f32 v10, v112, v111, v137
	ds_write_b32 v110, v10 offset:22528
	v_mul_f32_e32 v111, 0xbfb8aa3b, v138
	v_exp_f32_e32 v111, v111
	s_nop 0
	v_add_f32_e32 v111, 1.0, v111
	v_div_scale_f32 v112, s[42:43], v111, v111, v138
	v_rcp_f32_e32 v113, v112
	v_div_scale_f32 v114, vcc, v138, v111, v138
	v_fma_f32 v115, -v112, v113, 1.0
	v_fmac_f32_e32 v113, v115, v113
	v_mul_f32_e32 v115, v114, v113
	v_fma_f32 v116, -v112, v115, v114
	v_fmac_f32_e32 v115, v116, v113
	v_fma_f32 v112, -v112, v115, v114
	v_div_fmas_f32 v112, v112, v113, v115
	v_div_fixup_f32 v10, v112, v111, v138
	ds_write_b32 v110, v10 offset:24576
	v_mul_f32_e32 v111, 0xbfb8aa3b, v139
	v_exp_f32_e32 v111, v111
	s_nop 0
	v_add_f32_e32 v111, 1.0, v111
	v_div_scale_f32 v112, s[42:43], v111, v111, v139
	v_rcp_f32_e32 v113, v112
	v_div_scale_f32 v114, vcc, v139, v111, v139
	v_fma_f32 v115, -v112, v113, 1.0
	v_fmac_f32_e32 v113, v115, v113
	v_mul_f32_e32 v115, v114, v113
	v_fma_f32 v116, -v112, v115, v114
	v_fmac_f32_e32 v115, v116, v113
	v_fma_f32 v112, -v112, v115, v114
	v_div_fmas_f32 v112, v112, v113, v115
	v_div_fixup_f32 v10, v112, v111, v139
	ds_write_b32 v110, v10 offset:26624
	v_mul_f32_e32 v111, 0xbfb8aa3b, v140
	v_exp_f32_e32 v111, v111
	s_nop 0
	v_add_f32_e32 v111, 1.0, v111
	v_div_scale_f32 v112, s[42:43], v111, v111, v140
	v_rcp_f32_e32 v113, v112
	v_div_scale_f32 v114, vcc, v140, v111, v140
	v_fma_f32 v115, -v112, v113, 1.0
	v_fmac_f32_e32 v113, v115, v113
	v_mul_f32_e32 v115, v114, v113
	v_fma_f32 v116, -v112, v115, v114
	v_fmac_f32_e32 v115, v116, v113
	v_fma_f32 v112, -v112, v115, v114
	v_div_fmas_f32 v112, v112, v113, v115
	v_div_fixup_f32 v10, v112, v111, v140
	ds_write_b32 v110, v10 offset:28672
	v_mul_f32_e32 v111, 0xbfb8aa3b, v141
	v_exp_f32_e32 v111, v111
	s_nop 0
	v_add_f32_e32 v111, 1.0, v111
	v_div_scale_f32 v112, s[42:43], v111, v111, v141
	v_rcp_f32_e32 v113, v112
	v_div_scale_f32 v114, vcc, v141, v111, v141
	v_fma_f32 v115, -v112, v113, 1.0
	v_fmac_f32_e32 v113, v115, v113
	v_mul_f32_e32 v115, v114, v113
	v_fma_f32 v116, -v112, v115, v114
	v_fmac_f32_e32 v115, v116, v113
	v_fma_f32 v112, -v112, v115, v114
	v_div_fmas_f32 v112, v112, v113, v115
	v_div_fixup_f32 v10, v112, v111, v141
	ds_write_b32 v110, v10 offset:30720
	v_mul_f32_e32 v111, 0xbfb8aa3b, v142
	v_exp_f32_e32 v111, v111
	s_nop 0
	v_add_f32_e32 v111, 1.0, v111
	v_div_scale_f32 v112, s[42:43], v111, v111, v142
	v_rcp_f32_e32 v113, v112
	v_div_scale_f32 v114, vcc, v142, v111, v142
	v_fma_f32 v115, -v112, v113, 1.0
	v_fmac_f32_e32 v113, v115, v113
	v_mul_f32_e32 v115, v114, v113
	v_fma_f32 v116, -v112, v115, v114
	v_fmac_f32_e32 v115, v116, v113
	v_fma_f32 v112, -v112, v115, v114
	v_div_fmas_f32 v112, v112, v113, v115
	v_div_fixup_f32 v10, v112, v111, v142
	ds_write_b32 v110, v10 offset:32768
	v_mul_f32_e32 v111, 0xbfb8aa3b, v143
	v_exp_f32_e32 v111, v111
	s_nop 0
	v_add_f32_e32 v111, 1.0, v111
	v_div_scale_f32 v112, s[42:43], v111, v111, v143
	v_rcp_f32_e32 v113, v112
	v_div_scale_f32 v114, vcc, v143, v111, v143
	v_fma_f32 v115, -v112, v113, 1.0
	v_fmac_f32_e32 v113, v115, v113
	v_mul_f32_e32 v115, v114, v113
	v_fma_f32 v116, -v112, v115, v114
	v_fmac_f32_e32 v115, v116, v113
	v_fma_f32 v112, -v112, v115, v114
	v_div_fmas_f32 v112, v112, v113, v115
	v_div_fixup_f32 v10, v112, v111, v143
	ds_write_b32 v110, v10 offset:34816
.LBB0_58:
	s_or_b64 exec, exec, s[38:39]
	v_lshl_add_u32 v1, v14, 8, 0
	s_waitcnt lgkmcnt(0)
	s_barrier
	ds_read_b128 v[110:113], v1
	ds_read_b128 v[114:117], v1 offset:16
	ds_read_b128 v[118:121], v1 offset:32
	ds_read_b128 v[122:125], v1 offset:48
	v_lshl_add_u32 v10, v109, 2, 0
	s_movk_i32 s26, 0x480
	s_waitcnt vmcnt(63) lgkmcnt(2)
	v_mul_f32_e32 v12, v49, v115
	v_mul_f32_e32 v11, v52, v111
	v_fmac_f32_e32 v11, v50, v110
	v_fmac_f32_e32 v11, v51, v112
	v_fmac_f32_e32 v12, v46, v114
	v_fmac_f32_e32 v11, v48, v113
	s_waitcnt vmcnt(63)
	v_fmac_f32_e32 v12, v47, v116
	v_add_f32_e32 v11, 0, v11
	s_waitcnt vmcnt(63)
	v_fmac_f32_e32 v12, v9, v117
	v_add_f32_e32 v11, v11, v12
	s_waitcnt vmcnt(63) lgkmcnt(1)
	v_mul_f32_e32 v12, v60, v119
	v_fmac_f32_e32 v12, v58, v118
	s_waitcnt vmcnt(63)
	v_fmac_f32_e32 v12, v59, v120
	s_waitcnt vmcnt(63)
	v_fmac_f32_e32 v12, v56, v121
	ds_read_b128 v[110:113], v1 offset:64
	ds_read_b128 v[114:117], v1 offset:80
	v_add_f32_e32 v11, v11, v12
	s_waitcnt vmcnt(63) lgkmcnt(2)
	v_mul_f32_e32 v12, v57, v123
	v_fmac_f32_e32 v12, v55, v122
	s_waitcnt vmcnt(63)
	v_fmac_f32_e32 v12, v53, v124
	s_waitcnt vmcnt(63)
	v_fmac_f32_e32 v12, v54, v125
	v_add_f32_e32 v11, v11, v12
	s_waitcnt vmcnt(63) lgkmcnt(1)
	v_mul_f32_e32 v12, v68, v111
	v_fmac_f32_e32 v12, v64, v110
	s_waitcnt vmcnt(63)
	v_fmac_f32_e32 v12, v65, v112
	s_waitcnt vmcnt(63)
	v_fmac_f32_e32 v12, v66, v113
	ds_read_b128 v[110:113], v1 offset:96
	v_add_f32_e32 v11, v11, v12
	s_waitcnt vmcnt(63) lgkmcnt(1)
	v_mul_f32_e32 v12, v67, v115
	v_fmac_f32_e32 v12, v63, v114
	s_waitcnt vmcnt(63)
	v_fmac_f32_e32 v12, v61, v116
	s_waitcnt vmcnt(63)
	v_fmac_f32_e32 v12, v62, v117
	ds_read_b128 v[114:117], v1 offset:112
	v_add_f32_e32 v11, v11, v12
	s_waitcnt vmcnt(63) lgkmcnt(1)
	v_mul_f32_e32 v12, v76, v111
	v_fmac_f32_e32 v12, v72, v110
	s_waitcnt vmcnt(63)
	v_fmac_f32_e32 v12, v73, v112
	s_waitcnt vmcnt(63)
	v_fmac_f32_e32 v12, v74, v113
	ds_read_b128 v[110:113], v1 offset:128
	v_add_f32_e32 v11, v11, v12
	s_waitcnt vmcnt(63) lgkmcnt(1)
	v_mul_f32_e32 v12, v75, v115
	v_fmac_f32_e32 v12, v71, v114
	s_waitcnt vmcnt(63)
	v_fmac_f32_e32 v12, v69, v116
	s_waitcnt vmcnt(63)
	v_fmac_f32_e32 v12, v70, v117
	ds_read_b128 v[114:117], v1 offset:144
	v_add_f32_e32 v11, v11, v12
	s_waitcnt vmcnt(62) lgkmcnt(1)
	v_mul_f32_e32 v12, v84, v111
	v_fmac_f32_e32 v12, v80, v110
	s_waitcnt vmcnt(61)
	v_fmac_f32_e32 v12, v81, v112
	s_waitcnt vmcnt(60)
	v_fmac_f32_e32 v12, v82, v113
	ds_read_b128 v[110:113], v1 offset:160
	v_add_f32_e32 v11, v11, v12
	s_waitcnt vmcnt(58) lgkmcnt(1)
	v_mul_f32_e32 v12, v83, v115
	v_fmac_f32_e32 v12, v79, v114
	s_waitcnt vmcnt(57)
	v_fmac_f32_e32 v12, v77, v116
	s_waitcnt vmcnt(56)
	v_fmac_f32_e32 v12, v78, v117
	ds_read_b128 v[114:117], v1 offset:176
	v_add_f32_e32 v11, v11, v12
	s_waitcnt vmcnt(54) lgkmcnt(1)
	v_mul_f32_e32 v12, v92, v111
	v_fmac_f32_e32 v12, v88, v110
	s_waitcnt vmcnt(53)
	v_fmac_f32_e32 v12, v89, v112
	s_waitcnt vmcnt(52)
	v_fmac_f32_e32 v12, v90, v113
	ds_read_b128 v[110:113], v1 offset:192
	v_add_f32_e32 v11, v11, v12
	s_waitcnt vmcnt(50) lgkmcnt(1)
	v_mul_f32_e32 v12, v91, v115
	v_fmac_f32_e32 v12, v87, v114
	s_waitcnt vmcnt(49)
	v_fmac_f32_e32 v12, v85, v116
	s_waitcnt vmcnt(48)
	v_fmac_f32_e32 v12, v86, v117
	ds_read_b128 v[114:117], v1 offset:208
	v_add_f32_e32 v11, v11, v12
	s_waitcnt vmcnt(46) lgkmcnt(1)
	v_mul_f32_e32 v12, v100, v111
	v_fmac_f32_e32 v12, v96, v110
	s_waitcnt vmcnt(45)
	v_fmac_f32_e32 v12, v97, v112
	s_waitcnt vmcnt(44)
	v_fmac_f32_e32 v12, v98, v113
	ds_read_b128 v[110:113], v1 offset:224
	v_add_f32_e32 v11, v11, v12
	s_waitcnt vmcnt(42) lgkmcnt(1)
	v_mul_f32_e32 v12, v99, v115
	v_fmac_f32_e32 v12, v95, v114
	s_waitcnt vmcnt(41)
	v_fmac_f32_e32 v12, v93, v116
	s_waitcnt vmcnt(40)
	v_fmac_f32_e32 v12, v94, v117
	ds_read_b128 v[114:117], v1 offset:240
	v_add_f32_e32 v11, v11, v12
	s_waitcnt vmcnt(38) lgkmcnt(1)
	v_mul_f32_e32 v12, v108, v111
	v_fmac_f32_e32 v12, v104, v110
	s_waitcnt vmcnt(37)
	v_fmac_f32_e32 v12, v105, v112
	s_waitcnt vmcnt(36)
	v_fmac_f32_e32 v12, v106, v113
	v_add_f32_e32 v11, v11, v12
	s_waitcnt vmcnt(34) lgkmcnt(0)
	v_mul_f32_e32 v12, v107, v115
	v_fmac_f32_e32 v12, v102, v114
	s_waitcnt vmcnt(33)
	v_fmac_f32_e32 v12, v103, v116
	s_waitcnt vmcnt(32)
	v_fmac_f32_e32 v12, v101, v117
	v_add_f32_e32 v11, v11, v12
	v_mad_u64_u32 v[12:13], s[26:27], v14, s26, v[10:11]
	ds_write_b32 v12, v11 offset:36864
	ds_read_b128 v[110:113], v1 offset:4096
	ds_read_b128 v[114:117], v1 offset:4112
	ds_read_b128 v[118:121], v1 offset:4128
	ds_read_b128 v[122:125], v1 offset:4144
	s_movk_i32 s26, 0x120
	s_waitcnt lgkmcnt(3)
	v_mul_f32_e32 v11, v52, v111
	v_fmac_f32_e32 v11, v50, v110
	s_waitcnt lgkmcnt(2)
	v_mul_f32_e32 v13, v49, v115
	v_fmac_f32_e32 v11, v51, v112
	v_fmac_f32_e32 v13, v46, v114
	v_fmac_f32_e32 v11, v48, v113
	v_fmac_f32_e32 v13, v47, v116
	v_add_f32_e32 v11, 0, v11
	v_fmac_f32_e32 v13, v9, v117
	v_add_f32_e32 v11, v11, v13
	s_waitcnt lgkmcnt(1)
	v_mul_f32_e32 v13, v60, v119
	v_fmac_f32_e32 v13, v58, v118
	v_fmac_f32_e32 v13, v59, v120
	v_fmac_f32_e32 v13, v56, v121
	ds_read_b128 v[110:113], v1 offset:4160
	ds_read_b128 v[114:117], v1 offset:4176
	v_add_f32_e32 v11, v11, v13
	s_waitcnt lgkmcnt(2)
	v_mul_f32_e32 v13, v57, v123
	v_fmac_f32_e32 v13, v55, v122
	v_fmac_f32_e32 v13, v53, v124
	v_fmac_f32_e32 v13, v54, v125
	v_add_f32_e32 v11, v11, v13
	s_waitcnt lgkmcnt(1)
	v_mul_f32_e32 v13, v68, v111
	v_fmac_f32_e32 v13, v64, v110
	v_fmac_f32_e32 v13, v65, v112
	v_fmac_f32_e32 v13, v66, v113
	ds_read_b128 v[110:113], v1 offset:4192
	v_add_f32_e32 v11, v11, v13
	s_waitcnt lgkmcnt(1)
	v_mul_f32_e32 v13, v67, v115
	v_fmac_f32_e32 v13, v63, v114
	v_fmac_f32_e32 v13, v61, v116
	v_fmac_f32_e32 v13, v62, v117
	ds_read_b128 v[114:117], v1 offset:4208
	v_add_f32_e32 v11, v11, v13
	s_waitcnt lgkmcnt(1)
	v_mul_f32_e32 v13, v76, v111
	v_fmac_f32_e32 v13, v72, v110
	v_fmac_f32_e32 v13, v73, v112
	v_fmac_f32_e32 v13, v74, v113
	ds_read_b128 v[110:113], v1 offset:4224
	v_add_f32_e32 v11, v11, v13
	s_waitcnt lgkmcnt(1)
	v_mul_f32_e32 v13, v75, v115
	v_fmac_f32_e32 v13, v71, v114
	v_fmac_f32_e32 v13, v69, v116
	v_fmac_f32_e32 v13, v70, v117
	ds_read_b128 v[114:117], v1 offset:4240
	v_add_f32_e32 v11, v11, v13
	s_waitcnt lgkmcnt(1)
	v_mul_f32_e32 v13, v84, v111
	v_fmac_f32_e32 v13, v80, v110
	v_fmac_f32_e32 v13, v81, v112
	v_fmac_f32_e32 v13, v82, v113
	ds_read_b128 v[110:113], v1 offset:4256
	v_add_f32_e32 v11, v11, v13
	s_waitcnt lgkmcnt(1)
	v_mul_f32_e32 v13, v83, v115
	v_fmac_f32_e32 v13, v79, v114
	v_fmac_f32_e32 v13, v77, v116
	v_fmac_f32_e32 v13, v78, v117
	ds_read_b128 v[114:117], v1 offset:4272
	v_add_f32_e32 v11, v11, v13
	s_waitcnt lgkmcnt(1)
	v_mul_f32_e32 v13, v92, v111
	v_fmac_f32_e32 v13, v88, v110
	v_fmac_f32_e32 v13, v89, v112
	v_fmac_f32_e32 v13, v90, v113
	ds_read_b128 v[110:113], v1 offset:4288
	v_add_f32_e32 v11, v11, v13
	s_waitcnt lgkmcnt(1)
	v_mul_f32_e32 v13, v91, v115
	v_fmac_f32_e32 v13, v87, v114
	v_fmac_f32_e32 v13, v85, v116
	v_fmac_f32_e32 v13, v86, v117
	ds_read_b128 v[114:117], v1 offset:4304
	v_add_f32_e32 v11, v11, v13
	s_waitcnt lgkmcnt(1)
	v_mul_f32_e32 v13, v100, v111
	v_fmac_f32_e32 v13, v96, v110
	v_fmac_f32_e32 v13, v97, v112
	v_fmac_f32_e32 v13, v98, v113
	ds_read_b128 v[110:113], v1 offset:4320
	v_add_f32_e32 v11, v11, v13
	s_waitcnt lgkmcnt(1)
	v_mul_f32_e32 v13, v99, v115
	v_fmac_f32_e32 v13, v95, v114
	v_fmac_f32_e32 v13, v93, v116
	v_fmac_f32_e32 v13, v94, v117
	ds_read_b128 v[114:117], v1 offset:4336
	v_add_f32_e32 v11, v11, v13
	s_waitcnt lgkmcnt(1)
	v_mul_f32_e32 v13, v108, v111
	v_fmac_f32_e32 v13, v104, v110
	v_fmac_f32_e32 v13, v105, v112
	v_fmac_f32_e32 v13, v106, v113
	v_add_f32_e32 v11, v11, v13
	s_waitcnt lgkmcnt(0)
	v_mul_f32_e32 v13, v107, v115
	v_fmac_f32_e32 v13, v102, v114
	v_fmac_f32_e32 v13, v103, v116
	v_fmac_f32_e32 v13, v101, v117
	v_add_f32_e32 v11, v11, v13
	ds_write_b32 v12, v11 offset:36992
	ds_read_b128 v[110:113], v1 offset:8192
	ds_read_b128 v[114:117], v1 offset:8208
	ds_read_b128 v[118:121], v1 offset:8224
	ds_read_b128 v[122:125], v1 offset:8240
	v_cmp_gt_i32_e32 vcc, s26, v0
	s_waitcnt lgkmcnt(3)
	v_mul_f32_e32 v11, v52, v111
	v_fmac_f32_e32 v11, v50, v110
	s_waitcnt lgkmcnt(2)
	v_mul_f32_e32 v13, v49, v115
	v_fmac_f32_e32 v11, v51, v112
	v_fmac_f32_e32 v13, v46, v114
	v_fmac_f32_e32 v11, v48, v113
	v_fmac_f32_e32 v13, v47, v116
	v_add_f32_e32 v11, 0, v11
	v_fmac_f32_e32 v13, v9, v117
	v_add_f32_e32 v11, v11, v13
	s_waitcnt lgkmcnt(1)
	v_mul_f32_e32 v13, v60, v119
	v_fmac_f32_e32 v13, v58, v118
	v_fmac_f32_e32 v13, v59, v120
	v_fmac_f32_e32 v13, v56, v121
	ds_read_b128 v[110:113], v1 offset:8256
	ds_read_b128 v[114:117], v1 offset:8272
	v_add_f32_e32 v11, v11, v13
	s_waitcnt lgkmcnt(2)
	v_mul_f32_e32 v13, v57, v123
	v_fmac_f32_e32 v13, v55, v122
	v_fmac_f32_e32 v13, v53, v124
	v_fmac_f32_e32 v13, v54, v125
	v_add_f32_e32 v11, v11, v13
	s_waitcnt lgkmcnt(1)
	v_mul_f32_e32 v13, v68, v111
	v_fmac_f32_e32 v13, v64, v110
	v_fmac_f32_e32 v13, v65, v112
	v_fmac_f32_e32 v13, v66, v113
	ds_read_b128 v[110:113], v1 offset:8288
	v_add_f32_e32 v11, v11, v13
	s_waitcnt lgkmcnt(1)
	v_mul_f32_e32 v13, v67, v115
	v_fmac_f32_e32 v13, v63, v114
	v_fmac_f32_e32 v13, v61, v116
	v_fmac_f32_e32 v13, v62, v117
	ds_read_b128 v[114:117], v1 offset:8304
	v_add_f32_e32 v11, v11, v13
	s_waitcnt lgkmcnt(1)
	v_mul_f32_e32 v13, v76, v111
	v_fmac_f32_e32 v13, v72, v110
	v_fmac_f32_e32 v13, v73, v112
	v_fmac_f32_e32 v13, v74, v113
	ds_read_b128 v[110:113], v1 offset:8320
	v_add_f32_e32 v11, v11, v13
	s_waitcnt lgkmcnt(1)
	v_mul_f32_e32 v13, v75, v115
	v_fmac_f32_e32 v13, v71, v114
	v_fmac_f32_e32 v13, v69, v116
	v_fmac_f32_e32 v13, v70, v117
	ds_read_b128 v[114:117], v1 offset:8336
	v_add_f32_e32 v11, v11, v13
	s_waitcnt lgkmcnt(1)
	v_mul_f32_e32 v13, v84, v111
	v_fmac_f32_e32 v13, v80, v110
	v_fmac_f32_e32 v13, v81, v112
	v_fmac_f32_e32 v13, v82, v113
	ds_read_b128 v[110:113], v1 offset:8352
	v_add_f32_e32 v11, v11, v13
	s_waitcnt lgkmcnt(1)
	v_mul_f32_e32 v13, v83, v115
	v_fmac_f32_e32 v13, v79, v114
	v_fmac_f32_e32 v13, v77, v116
	v_fmac_f32_e32 v13, v78, v117
	ds_read_b128 v[114:117], v1 offset:8368
	v_add_f32_e32 v11, v11, v13
	s_waitcnt lgkmcnt(1)
	v_mul_f32_e32 v13, v92, v111
	v_fmac_f32_e32 v13, v88, v110
	v_fmac_f32_e32 v13, v89, v112
	v_fmac_f32_e32 v13, v90, v113
	ds_read_b128 v[110:113], v1 offset:8384
	v_add_f32_e32 v11, v11, v13
	s_waitcnt lgkmcnt(1)
	v_mul_f32_e32 v13, v91, v115
	v_fmac_f32_e32 v13, v87, v114
	v_fmac_f32_e32 v13, v85, v116
	v_fmac_f32_e32 v13, v86, v117
	ds_read_b128 v[114:117], v1 offset:8400
	v_add_f32_e32 v11, v11, v13
	s_waitcnt lgkmcnt(1)
	v_mul_f32_e32 v13, v100, v111
	v_fmac_f32_e32 v13, v96, v110
	v_fmac_f32_e32 v13, v97, v112
	v_fmac_f32_e32 v13, v98, v113
	ds_read_b128 v[110:113], v1 offset:8416
	v_add_f32_e32 v11, v11, v13
	s_waitcnt lgkmcnt(1)
	v_mul_f32_e32 v13, v99, v115
	v_fmac_f32_e32 v13, v95, v114
	v_fmac_f32_e32 v13, v93, v116
	v_fmac_f32_e32 v13, v94, v117
	ds_read_b128 v[114:117], v1 offset:8432
	v_add_f32_e32 v11, v11, v13
	s_waitcnt lgkmcnt(1)
	v_mul_f32_e32 v13, v108, v111
	v_fmac_f32_e32 v13, v104, v110
	v_fmac_f32_e32 v13, v105, v112
	v_fmac_f32_e32 v13, v106, v113
	v_add_f32_e32 v11, v11, v13
	s_waitcnt lgkmcnt(0)
	v_mul_f32_e32 v13, v107, v115
	v_fmac_f32_e32 v13, v102, v114
	v_fmac_f32_e32 v13, v103, v116
	v_fmac_f32_e32 v13, v101, v117
	v_add_f32_e32 v11, v11, v13
	ds_write_b32 v12, v11 offset:37120
	ds_read_b128 v[110:113], v1 offset:12288
	ds_read_b128 v[114:117], v1 offset:12304
	ds_read_b128 v[118:121], v1 offset:12320
	ds_read_b128 v[122:125], v1 offset:12336
	s_waitcnt lgkmcnt(3)
	v_mul_f32_e32 v11, v52, v111
	v_fmac_f32_e32 v11, v50, v110
	s_waitcnt lgkmcnt(2)
	v_mul_f32_e32 v13, v49, v115
	v_fmac_f32_e32 v11, v51, v112
	v_fmac_f32_e32 v13, v46, v114
	v_fmac_f32_e32 v11, v48, v113
	v_fmac_f32_e32 v13, v47, v116
	v_add_f32_e32 v11, 0, v11
	v_fmac_f32_e32 v13, v9, v117
	v_add_f32_e32 v11, v11, v13
	s_waitcnt lgkmcnt(1)
	v_mul_f32_e32 v13, v60, v119
	v_fmac_f32_e32 v13, v58, v118
	v_fmac_f32_e32 v13, v59, v120
	v_fmac_f32_e32 v13, v56, v121
	ds_read_b128 v[110:113], v1 offset:12352
	ds_read_b128 v[114:117], v1 offset:12368
	v_add_f32_e32 v11, v11, v13
	s_waitcnt lgkmcnt(2)
	v_mul_f32_e32 v13, v57, v123
	v_fmac_f32_e32 v13, v55, v122
	v_fmac_f32_e32 v13, v53, v124
	v_fmac_f32_e32 v13, v54, v125
	v_add_f32_e32 v11, v11, v13
	s_waitcnt lgkmcnt(1)
	v_mul_f32_e32 v13, v68, v111
	v_fmac_f32_e32 v13, v64, v110
	v_fmac_f32_e32 v13, v65, v112
	v_fmac_f32_e32 v13, v66, v113
	ds_read_b128 v[110:113], v1 offset:12384
	v_add_f32_e32 v11, v11, v13
	s_waitcnt lgkmcnt(1)
	v_mul_f32_e32 v13, v67, v115
	v_fmac_f32_e32 v13, v63, v114
	v_fmac_f32_e32 v13, v61, v116
	v_fmac_f32_e32 v13, v62, v117
	ds_read_b128 v[114:117], v1 offset:12400
	v_add_f32_e32 v11, v11, v13
	s_waitcnt lgkmcnt(1)
	v_mul_f32_e32 v13, v76, v111
	v_fmac_f32_e32 v13, v72, v110
	v_fmac_f32_e32 v13, v73, v112
	v_fmac_f32_e32 v13, v74, v113
	ds_read_b128 v[110:113], v1 offset:12416
	v_add_f32_e32 v11, v11, v13
	s_waitcnt lgkmcnt(1)
	v_mul_f32_e32 v13, v75, v115
	v_fmac_f32_e32 v13, v71, v114
	v_fmac_f32_e32 v13, v69, v116
	v_fmac_f32_e32 v13, v70, v117
	ds_read_b128 v[114:117], v1 offset:12432
	v_add_f32_e32 v11, v11, v13
	s_waitcnt lgkmcnt(1)
	v_mul_f32_e32 v13, v84, v111
	v_fmac_f32_e32 v13, v80, v110
	v_fmac_f32_e32 v13, v81, v112
	v_fmac_f32_e32 v13, v82, v113
	ds_read_b128 v[110:113], v1 offset:12448
	v_add_f32_e32 v11, v11, v13
	s_waitcnt lgkmcnt(1)
	v_mul_f32_e32 v13, v83, v115
	v_fmac_f32_e32 v13, v79, v114
	v_fmac_f32_e32 v13, v77, v116
	v_fmac_f32_e32 v13, v78, v117
	ds_read_b128 v[114:117], v1 offset:12464
	v_add_f32_e32 v11, v11, v13
	s_waitcnt lgkmcnt(1)
	v_mul_f32_e32 v13, v92, v111
	v_fmac_f32_e32 v13, v88, v110
	v_fmac_f32_e32 v13, v89, v112
	v_fmac_f32_e32 v13, v90, v113
	ds_read_b128 v[110:113], v1 offset:12480
	v_add_f32_e32 v11, v11, v13
	s_waitcnt lgkmcnt(1)
	v_mul_f32_e32 v13, v91, v115
	v_fmac_f32_e32 v13, v87, v114
	v_fmac_f32_e32 v13, v85, v116
	v_fmac_f32_e32 v13, v86, v117
	ds_read_b128 v[114:117], v1 offset:12496
	v_add_f32_e32 v11, v11, v13
	s_waitcnt lgkmcnt(1)
	v_mul_f32_e32 v13, v100, v111
	v_fmac_f32_e32 v13, v96, v110
	v_fmac_f32_e32 v13, v97, v112
	v_fmac_f32_e32 v13, v98, v113
	ds_read_b128 v[110:113], v1 offset:12512
	v_add_f32_e32 v11, v11, v13
	s_waitcnt lgkmcnt(1)
	v_mul_f32_e32 v13, v99, v115
	v_fmac_f32_e32 v13, v95, v114
	v_fmac_f32_e32 v13, v93, v116
	v_fmac_f32_e32 v13, v94, v117
	ds_read_b128 v[114:117], v1 offset:12528
	v_add_f32_e32 v11, v11, v13
	s_waitcnt lgkmcnt(1)
	v_mul_f32_e32 v13, v108, v111
	v_fmac_f32_e32 v13, v104, v110
	v_fmac_f32_e32 v13, v105, v112
	v_fmac_f32_e32 v13, v106, v113
	v_add_f32_e32 v11, v11, v13
	s_waitcnt lgkmcnt(0)
	v_mul_f32_e32 v13, v107, v115
	v_fmac_f32_e32 v13, v102, v114
	v_fmac_f32_e32 v13, v103, v116
	v_fmac_f32_e32 v13, v101, v117
	v_add_f32_e32 v11, v11, v13
	ds_write_b32 v12, v11 offset:37248
	ds_read_b128 v[110:113], v1 offset:16384
	ds_read_b128 v[114:117], v1 offset:16400
	ds_read_b128 v[118:121], v1 offset:16416
	ds_read_b128 v[122:125], v1 offset:16432
	s_waitcnt lgkmcnt(3)
	v_mul_f32_e32 v11, v52, v111
	v_fmac_f32_e32 v11, v50, v110
	s_waitcnt lgkmcnt(2)
	v_mul_f32_e32 v13, v49, v115
	v_fmac_f32_e32 v11, v51, v112
	v_fmac_f32_e32 v13, v46, v114
	v_fmac_f32_e32 v11, v48, v113
	v_fmac_f32_e32 v13, v47, v116
	v_add_f32_e32 v11, 0, v11
	v_fmac_f32_e32 v13, v9, v117
	v_add_f32_e32 v11, v11, v13
	s_waitcnt lgkmcnt(1)
	v_mul_f32_e32 v13, v60, v119
	v_fmac_f32_e32 v13, v58, v118
	v_fmac_f32_e32 v13, v59, v120
	v_fmac_f32_e32 v13, v56, v121
	ds_read_b128 v[110:113], v1 offset:16448
	ds_read_b128 v[114:117], v1 offset:16464
	v_add_f32_e32 v11, v11, v13
	s_waitcnt lgkmcnt(2)
	v_mul_f32_e32 v13, v57, v123
	v_fmac_f32_e32 v13, v55, v122
	v_fmac_f32_e32 v13, v53, v124
	v_fmac_f32_e32 v13, v54, v125
	v_add_f32_e32 v11, v11, v13
	s_waitcnt lgkmcnt(1)
	v_mul_f32_e32 v13, v68, v111
	v_fmac_f32_e32 v13, v64, v110
	v_fmac_f32_e32 v13, v65, v112
	v_fmac_f32_e32 v13, v66, v113
	ds_read_b128 v[110:113], v1 offset:16480
	v_add_f32_e32 v11, v11, v13
	s_waitcnt lgkmcnt(1)
	v_mul_f32_e32 v13, v67, v115
	v_fmac_f32_e32 v13, v63, v114
	v_fmac_f32_e32 v13, v61, v116
	v_fmac_f32_e32 v13, v62, v117
	ds_read_b128 v[114:117], v1 offset:16496
	v_add_f32_e32 v11, v11, v13
	s_waitcnt lgkmcnt(1)
	v_mul_f32_e32 v13, v76, v111
	v_fmac_f32_e32 v13, v72, v110
	v_fmac_f32_e32 v13, v73, v112
	v_fmac_f32_e32 v13, v74, v113
	ds_read_b128 v[110:113], v1 offset:16512
	v_add_f32_e32 v11, v11, v13
	s_waitcnt lgkmcnt(1)
	v_mul_f32_e32 v13, v75, v115
	v_fmac_f32_e32 v13, v71, v114
	v_fmac_f32_e32 v13, v69, v116
	v_fmac_f32_e32 v13, v70, v117
	ds_read_b128 v[114:117], v1 offset:16528
	v_add_f32_e32 v11, v11, v13
	s_waitcnt lgkmcnt(1)
	v_mul_f32_e32 v13, v84, v111
	v_fmac_f32_e32 v13, v80, v110
	v_fmac_f32_e32 v13, v81, v112
	v_fmac_f32_e32 v13, v82, v113
	ds_read_b128 v[110:113], v1 offset:16544
	v_add_f32_e32 v11, v11, v13
	s_waitcnt lgkmcnt(1)
	v_mul_f32_e32 v13, v83, v115
	v_fmac_f32_e32 v13, v79, v114
	v_fmac_f32_e32 v13, v77, v116
	v_fmac_f32_e32 v13, v78, v117
	ds_read_b128 v[114:117], v1 offset:16560
	v_add_f32_e32 v11, v11, v13
	s_waitcnt lgkmcnt(1)
	v_mul_f32_e32 v13, v92, v111
	v_fmac_f32_e32 v13, v88, v110
	v_fmac_f32_e32 v13, v89, v112
	v_fmac_f32_e32 v13, v90, v113
	ds_read_b128 v[110:113], v1 offset:16576
	v_add_f32_e32 v11, v11, v13
	s_waitcnt lgkmcnt(1)
	v_mul_f32_e32 v13, v91, v115
	v_fmac_f32_e32 v13, v87, v114
	v_fmac_f32_e32 v13, v85, v116
	v_fmac_f32_e32 v13, v86, v117
	ds_read_b128 v[114:117], v1 offset:16592
	v_add_f32_e32 v11, v11, v13
	s_waitcnt lgkmcnt(1)
	v_mul_f32_e32 v13, v100, v111
	v_fmac_f32_e32 v13, v96, v110
	v_fmac_f32_e32 v13, v97, v112
	v_fmac_f32_e32 v13, v98, v113
	ds_read_b128 v[110:113], v1 offset:16608
	v_add_f32_e32 v11, v11, v13
	s_waitcnt lgkmcnt(1)
	v_mul_f32_e32 v13, v99, v115
	v_fmac_f32_e32 v13, v95, v114
	v_fmac_f32_e32 v13, v93, v116
	v_fmac_f32_e32 v13, v94, v117
	ds_read_b128 v[114:117], v1 offset:16624
	v_add_f32_e32 v11, v11, v13
	s_waitcnt lgkmcnt(1)
	v_mul_f32_e32 v13, v108, v111
	v_fmac_f32_e32 v13, v104, v110
	v_fmac_f32_e32 v13, v105, v112
	v_fmac_f32_e32 v13, v106, v113
	v_add_f32_e32 v11, v11, v13
	s_waitcnt lgkmcnt(0)
	v_mul_f32_e32 v13, v107, v115
	v_fmac_f32_e32 v13, v102, v114
	v_fmac_f32_e32 v13, v103, v116
	v_fmac_f32_e32 v13, v101, v117
	v_add_f32_e32 v11, v11, v13
	ds_write_b32 v12, v11 offset:37376
	ds_read_b128 v[110:113], v1 offset:20480
	ds_read_b128 v[114:117], v1 offset:20496
	ds_read_b128 v[118:121], v1 offset:20512
	ds_read_b128 v[122:125], v1 offset:20528
	s_waitcnt lgkmcnt(3)
	v_mul_f32_e32 v11, v52, v111
	v_fmac_f32_e32 v11, v50, v110
	s_waitcnt lgkmcnt(2)
	v_mul_f32_e32 v13, v49, v115
	v_fmac_f32_e32 v11, v51, v112
	v_fmac_f32_e32 v13, v46, v114
	v_fmac_f32_e32 v11, v48, v113
	v_fmac_f32_e32 v13, v47, v116
	v_add_f32_e32 v11, 0, v11
	v_fmac_f32_e32 v13, v9, v117
	v_add_f32_e32 v11, v11, v13
	s_waitcnt lgkmcnt(1)
	v_mul_f32_e32 v13, v60, v119
	v_fmac_f32_e32 v13, v58, v118
	v_fmac_f32_e32 v13, v59, v120
	v_fmac_f32_e32 v13, v56, v121
	ds_read_b128 v[110:113], v1 offset:20544
	ds_read_b128 v[114:117], v1 offset:20560
	v_add_f32_e32 v11, v11, v13
	s_waitcnt lgkmcnt(2)
	v_mul_f32_e32 v13, v57, v123
	v_fmac_f32_e32 v13, v55, v122
	v_fmac_f32_e32 v13, v53, v124
	v_fmac_f32_e32 v13, v54, v125
	v_add_f32_e32 v11, v11, v13
	s_waitcnt lgkmcnt(1)
	v_mul_f32_e32 v13, v68, v111
	v_fmac_f32_e32 v13, v64, v110
	v_fmac_f32_e32 v13, v65, v112
	v_fmac_f32_e32 v13, v66, v113
	ds_read_b128 v[110:113], v1 offset:20576
	v_add_f32_e32 v11, v11, v13
	s_waitcnt lgkmcnt(1)
	v_mul_f32_e32 v13, v67, v115
	v_fmac_f32_e32 v13, v63, v114
	v_fmac_f32_e32 v13, v61, v116
	v_fmac_f32_e32 v13, v62, v117
	ds_read_b128 v[114:117], v1 offset:20592
	v_add_f32_e32 v11, v11, v13
	s_waitcnt lgkmcnt(1)
	v_mul_f32_e32 v13, v76, v111
	v_fmac_f32_e32 v13, v72, v110
	v_fmac_f32_e32 v13, v73, v112
	v_fmac_f32_e32 v13, v74, v113
	ds_read_b128 v[110:113], v1 offset:20608
	v_add_f32_e32 v11, v11, v13
	s_waitcnt lgkmcnt(1)
	v_mul_f32_e32 v13, v75, v115
	v_fmac_f32_e32 v13, v71, v114
	v_fmac_f32_e32 v13, v69, v116
	v_fmac_f32_e32 v13, v70, v117
	ds_read_b128 v[114:117], v1 offset:20624
	v_add_f32_e32 v11, v11, v13
	s_waitcnt lgkmcnt(1)
	v_mul_f32_e32 v13, v84, v111
	v_fmac_f32_e32 v13, v80, v110
	v_fmac_f32_e32 v13, v81, v112
	v_fmac_f32_e32 v13, v82, v113
	ds_read_b128 v[110:113], v1 offset:20640
	v_add_f32_e32 v11, v11, v13
	s_waitcnt lgkmcnt(1)
	v_mul_f32_e32 v13, v83, v115
	v_fmac_f32_e32 v13, v79, v114
	v_fmac_f32_e32 v13, v77, v116
	v_fmac_f32_e32 v13, v78, v117
	ds_read_b128 v[114:117], v1 offset:20656
	v_add_f32_e32 v11, v11, v13
	s_waitcnt lgkmcnt(1)
	v_mul_f32_e32 v13, v92, v111
	v_fmac_f32_e32 v13, v88, v110
	v_fmac_f32_e32 v13, v89, v112
	v_fmac_f32_e32 v13, v90, v113
	ds_read_b128 v[110:113], v1 offset:20672
	v_add_f32_e32 v11, v11, v13
	s_waitcnt lgkmcnt(1)
	v_mul_f32_e32 v13, v91, v115
	v_fmac_f32_e32 v13, v87, v114
	v_fmac_f32_e32 v13, v85, v116
	v_fmac_f32_e32 v13, v86, v117
	ds_read_b128 v[114:117], v1 offset:20688
	v_add_f32_e32 v11, v11, v13
	s_waitcnt lgkmcnt(1)
	v_mul_f32_e32 v13, v100, v111
	v_fmac_f32_e32 v13, v96, v110
	v_fmac_f32_e32 v13, v97, v112
	v_fmac_f32_e32 v13, v98, v113
	ds_read_b128 v[110:113], v1 offset:20704
	v_add_f32_e32 v11, v11, v13
	s_waitcnt lgkmcnt(1)
	v_mul_f32_e32 v13, v99, v115
	v_fmac_f32_e32 v13, v95, v114
	v_fmac_f32_e32 v13, v93, v116
	v_fmac_f32_e32 v13, v94, v117
	ds_read_b128 v[114:117], v1 offset:20720
	v_add_f32_e32 v11, v11, v13
	s_waitcnt lgkmcnt(1)
	v_mul_f32_e32 v13, v108, v111
	v_fmac_f32_e32 v13, v104, v110
	v_fmac_f32_e32 v13, v105, v112
	v_fmac_f32_e32 v13, v106, v113
	v_add_f32_e32 v11, v11, v13
	s_waitcnt lgkmcnt(0)
	v_mul_f32_e32 v13, v107, v115
	v_fmac_f32_e32 v13, v102, v114
	v_fmac_f32_e32 v13, v103, v116
	v_fmac_f32_e32 v13, v101, v117
	v_add_f32_e32 v11, v11, v13
	ds_write_b32 v12, v11 offset:37504
	ds_read_b128 v[110:113], v1 offset:24576
	ds_read_b128 v[114:117], v1 offset:24592
	ds_read_b128 v[118:121], v1 offset:24608
	ds_read_b128 v[122:125], v1 offset:24624
	s_waitcnt lgkmcnt(3)
	v_mul_f32_e32 v11, v52, v111
	v_fmac_f32_e32 v11, v50, v110
	s_waitcnt lgkmcnt(2)
	v_mul_f32_e32 v13, v49, v115
	v_fmac_f32_e32 v11, v51, v112
	v_fmac_f32_e32 v13, v46, v114
	v_fmac_f32_e32 v11, v48, v113
	v_fmac_f32_e32 v13, v47, v116
	v_add_f32_e32 v11, 0, v11
	v_fmac_f32_e32 v13, v9, v117
	v_add_f32_e32 v11, v11, v13
	s_waitcnt lgkmcnt(1)
	v_mul_f32_e32 v13, v60, v119
	v_fmac_f32_e32 v13, v58, v118
	v_fmac_f32_e32 v13, v59, v120
	v_fmac_f32_e32 v13, v56, v121
	ds_read_b128 v[110:113], v1 offset:24640
	ds_read_b128 v[114:117], v1 offset:24656
	v_add_f32_e32 v11, v11, v13
	s_waitcnt lgkmcnt(2)
	v_mul_f32_e32 v13, v57, v123
	v_fmac_f32_e32 v13, v55, v122
	v_fmac_f32_e32 v13, v53, v124
	v_fmac_f32_e32 v13, v54, v125
	v_add_f32_e32 v11, v11, v13
	s_waitcnt lgkmcnt(1)
	v_mul_f32_e32 v13, v68, v111
	v_fmac_f32_e32 v13, v64, v110
	v_fmac_f32_e32 v13, v65, v112
	v_fmac_f32_e32 v13, v66, v113
	ds_read_b128 v[110:113], v1 offset:24672
	v_add_f32_e32 v11, v11, v13
	s_waitcnt lgkmcnt(1)
	v_mul_f32_e32 v13, v67, v115
	v_fmac_f32_e32 v13, v63, v114
	v_fmac_f32_e32 v13, v61, v116
	v_fmac_f32_e32 v13, v62, v117
	ds_read_b128 v[114:117], v1 offset:24688
	v_add_f32_e32 v11, v11, v13
	s_waitcnt lgkmcnt(1)
	v_mul_f32_e32 v13, v76, v111
	v_fmac_f32_e32 v13, v72, v110
	v_fmac_f32_e32 v13, v73, v112
	v_fmac_f32_e32 v13, v74, v113
	ds_read_b128 v[110:113], v1 offset:24704
	v_add_f32_e32 v11, v11, v13
	s_waitcnt lgkmcnt(1)
	v_mul_f32_e32 v13, v75, v115
	v_fmac_f32_e32 v13, v71, v114
	v_fmac_f32_e32 v13, v69, v116
	v_fmac_f32_e32 v13, v70, v117
	ds_read_b128 v[114:117], v1 offset:24720
	v_add_f32_e32 v11, v11, v13
	s_waitcnt lgkmcnt(1)
	v_mul_f32_e32 v13, v84, v111
	v_fmac_f32_e32 v13, v80, v110
	v_fmac_f32_e32 v13, v81, v112
	v_fmac_f32_e32 v13, v82, v113
	ds_read_b128 v[110:113], v1 offset:24736
	v_add_f32_e32 v11, v11, v13
	s_waitcnt lgkmcnt(1)
	v_mul_f32_e32 v13, v83, v115
	v_fmac_f32_e32 v13, v79, v114
	v_fmac_f32_e32 v13, v77, v116
	v_fmac_f32_e32 v13, v78, v117
	ds_read_b128 v[114:117], v1 offset:24752
	v_add_f32_e32 v11, v11, v13
	s_waitcnt lgkmcnt(1)
	v_mul_f32_e32 v13, v92, v111
	v_fmac_f32_e32 v13, v88, v110
	v_fmac_f32_e32 v13, v89, v112
	v_fmac_f32_e32 v13, v90, v113
	ds_read_b128 v[110:113], v1 offset:24768
	v_add_f32_e32 v11, v11, v13
	s_waitcnt lgkmcnt(1)
	v_mul_f32_e32 v13, v91, v115
	v_fmac_f32_e32 v13, v87, v114
	v_fmac_f32_e32 v13, v85, v116
	v_fmac_f32_e32 v13, v86, v117
	ds_read_b128 v[114:117], v1 offset:24784
	v_add_f32_e32 v11, v11, v13
	s_waitcnt lgkmcnt(1)
	v_mul_f32_e32 v13, v100, v111
	v_fmac_f32_e32 v13, v96, v110
	v_fmac_f32_e32 v13, v97, v112
	v_fmac_f32_e32 v13, v98, v113
	ds_read_b128 v[110:113], v1 offset:24800
	v_add_f32_e32 v11, v11, v13
	s_waitcnt lgkmcnt(1)
	v_mul_f32_e32 v13, v99, v115
	v_fmac_f32_e32 v13, v95, v114
	v_fmac_f32_e32 v13, v93, v116
	v_fmac_f32_e32 v13, v94, v117
	ds_read_b128 v[114:117], v1 offset:24816
	v_add_f32_e32 v11, v11, v13
	s_waitcnt lgkmcnt(1)
	v_mul_f32_e32 v13, v108, v111
	v_fmac_f32_e32 v13, v104, v110
	v_fmac_f32_e32 v13, v105, v112
	v_fmac_f32_e32 v13, v106, v113
	v_add_f32_e32 v11, v11, v13
	s_waitcnt lgkmcnt(0)
	v_mul_f32_e32 v13, v107, v115
	v_fmac_f32_e32 v13, v102, v114
	v_fmac_f32_e32 v13, v103, v116
	v_fmac_f32_e32 v13, v101, v117
	v_add_f32_e32 v11, v11, v13
	ds_write_b32 v12, v11 offset:37632
	ds_read_b128 v[110:113], v1 offset:28672
	ds_read_b128 v[114:117], v1 offset:28688
	ds_read_b128 v[118:121], v1 offset:28704
	ds_read_b128 v[122:125], v1 offset:28720
	s_waitcnt lgkmcnt(3)
	v_mul_f32_e32 v11, v52, v111
	v_fmac_f32_e32 v11, v50, v110
	s_waitcnt lgkmcnt(2)
	v_mul_f32_e32 v13, v49, v115
	v_fmac_f32_e32 v11, v51, v112
	v_fmac_f32_e32 v13, v46, v114
	v_fmac_f32_e32 v11, v48, v113
	v_fmac_f32_e32 v13, v47, v116
	v_add_f32_e32 v11, 0, v11
	v_fmac_f32_e32 v13, v9, v117
	v_add_f32_e32 v11, v11, v13
	s_waitcnt lgkmcnt(1)
	v_mul_f32_e32 v13, v60, v119
	v_fmac_f32_e32 v13, v58, v118
	v_fmac_f32_e32 v13, v59, v120
	v_fmac_f32_e32 v13, v56, v121
	ds_read_b128 v[110:113], v1 offset:28736
	ds_read_b128 v[114:117], v1 offset:28752
	v_add_f32_e32 v11, v11, v13
	s_waitcnt lgkmcnt(2)
	v_mul_f32_e32 v13, v57, v123
	v_fmac_f32_e32 v13, v55, v122
	v_fmac_f32_e32 v13, v53, v124
	v_fmac_f32_e32 v13, v54, v125
	v_add_f32_e32 v11, v11, v13
	s_waitcnt lgkmcnt(1)
	v_mul_f32_e32 v13, v68, v111
	v_fmac_f32_e32 v13, v64, v110
	v_fmac_f32_e32 v13, v65, v112
	v_fmac_f32_e32 v13, v66, v113
	ds_read_b128 v[110:113], v1 offset:28768
	v_add_f32_e32 v11, v11, v13
	s_waitcnt lgkmcnt(1)
	v_mul_f32_e32 v13, v67, v115
	v_fmac_f32_e32 v13, v63, v114
	v_fmac_f32_e32 v13, v61, v116
	v_fmac_f32_e32 v13, v62, v117
	ds_read_b128 v[114:117], v1 offset:28784
	v_add_f32_e32 v11, v11, v13
	s_waitcnt lgkmcnt(1)
	v_mul_f32_e32 v13, v76, v111
	v_fmac_f32_e32 v13, v72, v110
	v_fmac_f32_e32 v13, v73, v112
	v_fmac_f32_e32 v13, v74, v113
	ds_read_b128 v[110:113], v1 offset:28800
	v_add_f32_e32 v11, v11, v13
	s_waitcnt lgkmcnt(1)
	v_mul_f32_e32 v13, v75, v115
	v_fmac_f32_e32 v13, v71, v114
	v_fmac_f32_e32 v13, v69, v116
	v_fmac_f32_e32 v13, v70, v117
	ds_read_b128 v[114:117], v1 offset:28816
	v_add_f32_e32 v11, v11, v13
	s_waitcnt lgkmcnt(1)
	v_mul_f32_e32 v13, v84, v111
	v_fmac_f32_e32 v13, v80, v110
	v_fmac_f32_e32 v13, v81, v112
	v_fmac_f32_e32 v13, v82, v113
	ds_read_b128 v[110:113], v1 offset:28832
	v_add_f32_e32 v11, v11, v13
	s_waitcnt lgkmcnt(1)
	v_mul_f32_e32 v13, v83, v115
	v_fmac_f32_e32 v13, v79, v114
	v_fmac_f32_e32 v13, v77, v116
	v_fmac_f32_e32 v13, v78, v117
	ds_read_b128 v[114:117], v1 offset:28848
	v_add_f32_e32 v11, v11, v13
	s_waitcnt lgkmcnt(1)
	v_mul_f32_e32 v13, v92, v111
	v_fmac_f32_e32 v13, v88, v110
	v_fmac_f32_e32 v13, v89, v112
	v_fmac_f32_e32 v13, v90, v113
	ds_read_b128 v[110:113], v1 offset:28864
	v_add_f32_e32 v11, v11, v13
	s_waitcnt lgkmcnt(1)
	v_mul_f32_e32 v13, v91, v115
	v_fmac_f32_e32 v13, v87, v114
	v_fmac_f32_e32 v13, v85, v116
	v_fmac_f32_e32 v13, v86, v117
	ds_read_b128 v[114:117], v1 offset:28880
	v_add_f32_e32 v11, v11, v13
	s_waitcnt lgkmcnt(1)
	v_mul_f32_e32 v13, v100, v111
	v_fmac_f32_e32 v13, v96, v110
	v_fmac_f32_e32 v13, v97, v112
	v_fmac_f32_e32 v13, v98, v113
	ds_read_b128 v[110:113], v1 offset:28896
	v_add_f32_e32 v11, v11, v13
	s_waitcnt lgkmcnt(1)
	v_mul_f32_e32 v13, v99, v115
	v_fmac_f32_e32 v13, v95, v114
	v_fmac_f32_e32 v13, v93, v116
	v_fmac_f32_e32 v13, v94, v117
	ds_read_b128 v[114:117], v1 offset:28912
	v_add_f32_e32 v11, v11, v13
	s_waitcnt lgkmcnt(1)
	v_mul_f32_e32 v13, v108, v111
	v_fmac_f32_e32 v13, v104, v110
	v_fmac_f32_e32 v13, v105, v112
	v_fmac_f32_e32 v13, v106, v113
	v_add_f32_e32 v11, v11, v13
	s_waitcnt lgkmcnt(0)
	v_mul_f32_e32 v13, v107, v115
	v_fmac_f32_e32 v13, v102, v114
	v_fmac_f32_e32 v13, v103, v116
	v_fmac_f32_e32 v13, v101, v117
	v_add_f32_e32 v11, v11, v13
	ds_write_b32 v12, v11 offset:37760
	ds_read_b128 v[110:113], v1 offset:32768
	ds_read_b128 v[114:117], v1 offset:32784
	ds_read_b128 v[118:121], v1 offset:32800
	ds_read_b128 v[122:125], v1 offset:32816
	s_waitcnt lgkmcnt(3)
	v_mul_f32_e32 v11, v52, v111
	v_fmac_f32_e32 v11, v50, v110
	s_waitcnt lgkmcnt(2)
	v_mul_f32_e32 v13, v49, v115
	v_fmac_f32_e32 v11, v51, v112
	v_fmac_f32_e32 v13, v46, v114
	v_fmac_f32_e32 v11, v48, v113
	v_fmac_f32_e32 v13, v47, v116
	v_add_f32_e32 v11, 0, v11
	v_fmac_f32_e32 v13, v9, v117
	v_add_f32_e32 v9, v11, v13
	s_waitcnt lgkmcnt(1)
	v_mul_f32_e32 v11, v60, v119
	v_fmac_f32_e32 v11, v58, v118
	v_fmac_f32_e32 v11, v59, v120
	v_fmac_f32_e32 v11, v56, v121
	ds_read_b128 v[46:49], v1 offset:32832
	v_add_f32_e32 v9, v9, v11
	s_waitcnt lgkmcnt(1)
	v_mul_f32_e32 v11, v57, v123
	v_fmac_f32_e32 v11, v55, v122
	v_fmac_f32_e32 v11, v53, v124
	v_fmac_f32_e32 v11, v54, v125
	ds_read_b128 v[50:53], v1 offset:32848
	v_add_f32_e32 v9, v9, v11
	s_waitcnt lgkmcnt(1)
	v_mul_f32_e32 v11, v68, v47
	v_fmac_f32_e32 v11, v64, v46
	v_fmac_f32_e32 v11, v65, v48
	v_fmac_f32_e32 v11, v66, v49
	ds_read_b128 v[46:49], v1 offset:32864
	v_add_f32_e32 v9, v9, v11
	s_waitcnt lgkmcnt(1)
	v_mul_f32_e32 v11, v67, v51
	v_fmac_f32_e32 v11, v63, v50
	v_fmac_f32_e32 v11, v61, v52
	v_fmac_f32_e32 v11, v62, v53
	ds_read_b128 v[50:53], v1 offset:32880
	v_add_f32_e32 v9, v9, v11
	s_waitcnt lgkmcnt(1)
	v_mul_f32_e32 v11, v76, v47
	v_fmac_f32_e32 v11, v72, v46
	v_fmac_f32_e32 v11, v73, v48
	v_fmac_f32_e32 v11, v74, v49
	ds_read_b128 v[46:49], v1 offset:32896
	v_add_f32_e32 v9, v9, v11
	s_waitcnt lgkmcnt(1)
	v_mul_f32_e32 v11, v75, v51
	v_fmac_f32_e32 v11, v71, v50
	v_fmac_f32_e32 v11, v69, v52
	v_fmac_f32_e32 v11, v70, v53
	ds_read_b128 v[50:53], v1 offset:32912
	v_add_f32_e32 v9, v9, v11
	s_waitcnt lgkmcnt(1)
	v_mul_f32_e32 v11, v84, v47
	v_fmac_f32_e32 v11, v80, v46
	v_fmac_f32_e32 v11, v81, v48
	v_fmac_f32_e32 v11, v82, v49
	ds_read_b128 v[46:49], v1 offset:32928
	v_add_f32_e32 v9, v9, v11
	s_waitcnt lgkmcnt(1)
	v_mul_f32_e32 v11, v83, v51
	v_fmac_f32_e32 v11, v79, v50
	v_fmac_f32_e32 v11, v77, v52
	v_fmac_f32_e32 v11, v78, v53
	ds_read_b128 v[50:53], v1 offset:32944
	v_add_f32_e32 v9, v9, v11
	s_waitcnt lgkmcnt(1)
	v_mul_f32_e32 v11, v92, v47
	v_fmac_f32_e32 v11, v88, v46
	v_fmac_f32_e32 v11, v89, v48
	v_fmac_f32_e32 v11, v90, v49
	ds_read_b128 v[46:49], v1 offset:32960
	v_add_f32_e32 v9, v9, v11
	s_waitcnt lgkmcnt(1)
	v_mul_f32_e32 v11, v91, v51
	v_fmac_f32_e32 v11, v87, v50
	v_fmac_f32_e32 v11, v85, v52
	v_fmac_f32_e32 v11, v86, v53
	ds_read_b128 v[50:53], v1 offset:32976
	v_add_f32_e32 v9, v9, v11
	s_waitcnt lgkmcnt(1)
	v_mul_f32_e32 v11, v100, v47
	v_fmac_f32_e32 v11, v96, v46
	v_fmac_f32_e32 v11, v97, v48
	v_fmac_f32_e32 v11, v98, v49
	ds_read_b128 v[46:49], v1 offset:32992
	v_add_f32_e32 v9, v9, v11
	s_waitcnt lgkmcnt(1)
	v_mul_f32_e32 v11, v99, v51
	v_fmac_f32_e32 v11, v95, v50
	v_fmac_f32_e32 v11, v93, v52
	v_fmac_f32_e32 v11, v94, v53
	ds_read_b128 v[50:53], v1 offset:33008
	s_waitcnt lgkmcnt(1)
	v_mul_f32_e32 v1, v108, v47
	v_fmac_f32_e32 v1, v104, v46
	v_fmac_f32_e32 v1, v105, v48
	v_add_f32_e32 v9, v9, v11
	v_fmac_f32_e32 v1, v106, v49
	v_add_f32_e32 v1, v9, v1
	s_waitcnt lgkmcnt(0)
	v_mul_f32_e32 v9, v107, v51
	v_fmac_f32_e32 v9, v102, v50
	v_fmac_f32_e32 v9, v103, v52
	v_fmac_f32_e32 v9, v101, v53
	v_add_f32_e32 v1, v1, v9
	ds_write_b32 v12, v1 offset:37888
	s_waitcnt lgkmcnt(0)
	s_barrier
	s_and_saveexec_b64 s[34:35], vcc
	s_cbranch_execz .LBB0_60
	v_mov_b32_e32 v12, s12
	v_mov_b32_e32 v13, s13
	v_ashrrev_i32_e32 v9, 31, v8
	v_lshl_add_u64 v[8:9], v[8:9], 2, v[12:13]
	v_mov_b32_e32 v1, v144
	v_lshl_add_u32 v8, v14, 7, v10
	v_mad_i32_i24 v9, v15, 9, v14
	ds_read_b32 v10, v8 offset:36864
	ds_read_b32 v11, v8 offset:38016
	ds_read_b32 v12, v8 offset:39168
	ds_read_b32 v13, v8 offset:40320
	ds_read_b32 v14, v8 offset:41472
	ds_read_b32 v15, v8 offset:42624
	ds_read_b32 v46, v8 offset:43776
	ds_read_b32 v47, v8 offset:44928
	ds_read_b32 v48, v8 offset:46080
	ds_read_b32 v49, v8 offset:47232
	ds_read_b32 v50, v8 offset:48384
	ds_read_b32 v51, v8 offset:49536
	ds_read_b32 v52, v8 offset:50688
	ds_read_b32 v53, v8 offset:51840
	ds_read_b32 v54, v8 offset:52992
	ds_read_b32 v55, v8 offset:54144
	s_movk_i32 s12, 0xc00
	v_mad_u64_u32 v[8:9], s[12:13], v9, s12, v[6:7]
	v_ashrrev_i32_e32 v9, 31, v8
	v_lshl_add_u64 v[8:9], v[8:9], 2, s[16:17]
	v_add_co_u32_e32 v8, vcc, 0x100000, v8
	s_waitcnt lgkmcnt(14)
	v_add_f32_e32 v1, v1, v10
	v_add_f32_e32 v1, v1, v11
	s_waitcnt lgkmcnt(13)
	v_add_f32_e32 v1, v1, v12
	s_waitcnt lgkmcnt(12)
	v_add_f32_e32 v1, v1, v13
	s_waitcnt lgkmcnt(11)
	v_add_f32_e32 v1, v1, v14
	s_waitcnt lgkmcnt(10)
	v_add_f32_e32 v1, v1, v15
	s_waitcnt lgkmcnt(9)
	v_add_f32_e32 v1, v1, v46
	s_waitcnt lgkmcnt(8)
	v_add_f32_e32 v1, v1, v47
	s_waitcnt lgkmcnt(7)
	v_add_f32_e32 v1, v1, v48
	s_waitcnt lgkmcnt(6)
	v_add_f32_e32 v1, v1, v49
	s_waitcnt lgkmcnt(5)
	v_add_f32_e32 v1, v1, v50
	s_waitcnt lgkmcnt(4)
	v_add_f32_e32 v1, v1, v51
	s_waitcnt lgkmcnt(3)
	v_add_f32_e32 v1, v1, v52
	s_waitcnt lgkmcnt(2)
	v_add_f32_e32 v1, v1, v53
	s_waitcnt lgkmcnt(1)
	v_add_f32_e32 v1, v1, v54
	s_waitcnt lgkmcnt(0)
	v_add_f32_e32 v1, v1, v55
	v_addc_co_u32_e32 v9, vcc, 0, v9, vcc
	global_store_dword v[8:9], v1, off sc1
